# k10 + byte-neutral mid-segment LDS drain in the W_o and down K-loops' SP1 load segments (8 B reads, drain, 8 A reads) by dropping the M0 hazard nop via reordering
# baseline (speedup 1.0000x reference)
.LBB0_559:
	s_add_u32 s0, s8, 0x100
	s_addc_u32 s1, s9, 0
	s_add_i32 s35, 0, 0x10000
	s_cmp_eq_u32 s34, 28
	s_cselect_b32 s13, s3, s1
	s_cselect_b32 s12, s18, s0
	s_cselect_b32 s11, s19, s33
	s_cselect_b32 s10, s22, s23
	s_add_i32 s36, 0, 0x14000
	v_add_u32_e32 v142, s35, v210
	v_add_u32_e32 v158, s36, v210
	ds_read_b128 v[130:133], v142
	ds_read_b128 v[134:137], v142 offset:1024
	ds_read_b128 v[138:141], v142 offset:2048
	ds_read_b128 v[142:145], v142 offset:3072
	ds_read_b128 v[146:149], v158
	ds_read_b128 v[150:153], v158 offset:1024
	ds_read_b128 v[154:157], v158 offset:2048
	ds_read_b128 v[158:161], v158 offset:3072
	v_lshl_add_u64 v[198:199], s[8:9], 0, v[190:191]
	s_add_i32 m0, s21, 0xc000
	s_waitcnt lgkmcnt(0)
	ds_read_b128 v[162:165], v220
	ds_read_b128 v[166:169], v220 offset:1024
	ds_read_b128 v[170:173], v220 offset:2048
	ds_read_b128 v[174:177], v220 offset:3072
	ds_read_b128 v[178:181], v220 offset:4096
	ds_read_b128 v[182:185], v220 offset:5120
	ds_read_b128 v[194:197], v220 offset:6144
	ds_read_b128 v[222:225], v220 offset:7168
	global_load_lds_dwordx4 v[198:199], off
	s_add_i32 m0, s21, 0xe000
	v_lshl_add_u64 v[198:199], s[8:9], 0, v[192:193]
	global_load_lds_dwordx4 v[198:199], off
	s_waitcnt vmcnt(8)
	s_waitcnt lgkmcnt(0)
	s_barrier
	s_setprio 1
	s_waitcnt lgkmcnt(0)
	v_mfma_f32_16x16x32_bf16 v[126:129], v[130:133], v[162:165], v[126:129]
	v_mfma_f32_16x16x32_bf16 v[122:125], v[138:141], v[162:165], v[122:125]
	v_mfma_f32_16x16x32_bf16 v[110:113], v[130:133], v[170:173], v[110:113]
	v_mfma_f32_16x16x32_bf16 v[106:109], v[138:141], v[170:173], v[106:109]
	v_mfma_f32_16x16x32_bf16 v[94:97], v[130:133], v[178:181], v[94:97]
	v_mfma_f32_16x16x32_bf16 v[90:93], v[138:141], v[178:181], v[90:93]
	v_mfma_f32_16x16x32_bf16 v[78:81], v[130:133], v[194:197], v[78:81]
	v_mfma_f32_16x16x32_bf16 v[74:77], v[138:141], v[194:197], v[74:77]
	v_mfma_f32_16x16x32_bf16 v[126:129], v[134:137], v[166:169], v[126:129]
	v_mfma_f32_16x16x32_bf16 v[122:125], v[142:145], v[166:169], v[122:125]
	v_mfma_f32_16x16x32_bf16 v[110:113], v[134:137], v[174:177], v[110:113]
	v_mfma_f32_16x16x32_bf16 v[106:109], v[142:145], v[174:177], v[106:109]
	v_mfma_f32_16x16x32_bf16 v[94:97], v[134:137], v[182:185], v[94:97]
	v_mfma_f32_16x16x32_bf16 v[90:93], v[142:145], v[182:185], v[90:93]
	v_mfma_f32_16x16x32_bf16 v[78:81], v[134:137], v[222:225], v[78:81]
	v_mfma_f32_16x16x32_bf16 v[74:77], v[142:145], v[222:225], v[74:77]
	s_setprio 0
	s_setprio 1
	v_mfma_f32_16x16x32_bf16 v[118:121], v[146:149], v[162:165], v[118:121]
	v_mfma_f32_16x16x32_bf16 v[114:117], v[154:157], v[162:165], v[114:117]
	v_mfma_f32_16x16x32_bf16 v[102:105], v[146:149], v[170:173], v[102:105]
	v_mfma_f32_16x16x32_bf16 v[98:101], v[154:157], v[170:173], v[98:101]
	v_mfma_f32_16x16x32_bf16 v[86:89], v[146:149], v[178:181], v[86:89]
	v_mfma_f32_16x16x32_bf16 v[82:85], v[154:157], v[178:181], v[82:85]
	v_mfma_f32_16x16x32_bf16 v[70:73], v[146:149], v[194:197], v[70:73]
	v_mfma_f32_16x16x32_bf16 v[66:69], v[154:157], v[194:197], v[66:69]
	v_mfma_f32_16x16x32_bf16 v[118:121], v[150:153], v[166:169], v[118:121]
	v_mfma_f32_16x16x32_bf16 v[114:117], v[158:161], v[166:169], v[114:117]
	v_mfma_f32_16x16x32_bf16 v[102:105], v[150:153], v[174:177], v[102:105]
	v_mfma_f32_16x16x32_bf16 v[98:101], v[158:161], v[174:177], v[98:101]
	v_mfma_f32_16x16x32_bf16 v[86:89], v[150:153], v[182:185], v[86:89]
	v_mfma_f32_16x16x32_bf16 v[82:85], v[158:161], v[182:185], v[82:85]
	v_mfma_f32_16x16x32_bf16 v[70:73], v[150:153], v[222:225], v[70:73]
	v_mfma_f32_16x16x32_bf16 v[66:69], v[158:161], v[222:225], v[66:69]
	s_setprio 0
	s_barrier
	s_add_i32 s8, s35, s14
	v_lshl_add_u64 v[198:199], s[10:11], 0, v[188:189]
	s_mov_b32 m0, s8
	ds_read_b128 v[162:165], v220 offset:16384
	ds_read_b128 v[166:169], v220 offset:17408
	ds_read_b128 v[170:173], v220 offset:18432
	ds_read_b128 v[174:177], v220 offset:19456
	ds_read_b128 v[178:181], v220 offset:20480
	ds_read_b128 v[182:185], v220 offset:21504
	ds_read_b128 v[194:197], v220 offset:22528
	ds_read_b128 v[222:225], v220 offset:23552
	global_load_lds_dwordx4 v[198:199], off
	s_add_i32 m0, s8, 0x2000
	s_add_u32 s8, s10, 0x80000
	v_lshl_add_u64 v[208:209], s[10:11], 0, v[186:187]
	s_addc_u32 s9, s11, 0
	s_add_i32 s35, s36, s14
	global_load_lds_dwordx4 v[208:209], off
	v_lshl_add_u64 v[226:227], s[8:9], 0, v[188:189]
	s_mov_b32 m0, s35
	v_lshl_add_u64 v[228:229], s[12:13], 0, v[186:187]
	global_load_lds_dwordx4 v[226:227], off
	v_lshl_add_u64 v[226:227], s[8:9], 0, v[186:187]
	s_add_i32 m0, s35, 0x2000
	s_nop 0
	global_load_lds_dwordx4 v[226:227], off
	v_lshl_add_u64 v[226:227], s[12:13], 0, v[188:189]
	s_mov_b32 m0, s21
	s_nop 0
	global_load_lds_dwordx4 v[226:227], off
	s_mov_b32 m0, s26
	s_nop 0
	global_load_lds_dwordx4 v[228:229], off
	s_waitcnt vmcnt(8)
	s_waitcnt lgkmcnt(0)
	s_barrier
	s_setprio 1
	s_waitcnt lgkmcnt(0)
	v_mfma_f32_16x16x32_bf16 v[62:65], v[130:133], v[162:165], v[62:65]
	v_mfma_f32_16x16x32_bf16 v[58:61], v[138:141], v[162:165], v[58:61]
	v_mfma_f32_16x16x32_bf16 v[46:49], v[130:133], v[170:173], v[46:49]
	v_mfma_f32_16x16x32_bf16 v[42:45], v[138:141], v[170:173], v[42:45]
	v_mfma_f32_16x16x32_bf16 v[30:33], v[130:133], v[178:181], v[30:33]
	v_mfma_f32_16x16x32_bf16 v[26:29], v[138:141], v[178:181], v[26:29]
	v_mfma_f32_16x16x32_bf16 v[14:17], v[130:133], v[194:197], v[14:17]
	v_mfma_f32_16x16x32_bf16 v[10:13], v[138:141], v[194:197], v[10:13]
	v_mfma_f32_16x16x32_bf16 v[62:65], v[134:137], v[166:169], v[62:65]
	v_mfma_f32_16x16x32_bf16 v[58:61], v[142:145], v[166:169], v[58:61]
	v_mfma_f32_16x16x32_bf16 v[46:49], v[134:137], v[174:177], v[46:49]
	v_mfma_f32_16x16x32_bf16 v[42:45], v[142:145], v[174:177], v[42:45]
	v_mfma_f32_16x16x32_bf16 v[30:33], v[134:137], v[182:185], v[30:33]
	v_mfma_f32_16x16x32_bf16 v[26:29], v[142:145], v[182:185], v[26:29]
	v_mfma_f32_16x16x32_bf16 v[14:17], v[134:137], v[222:225], v[14:17]
	v_mfma_f32_16x16x32_bf16 v[10:13], v[142:145], v[222:225], v[10:13]
	s_setprio 0
	s_setprio 1
	v_mfma_f32_16x16x32_bf16 v[54:57], v[146:149], v[162:165], v[54:57]
	v_mfma_f32_16x16x32_bf16 v[50:53], v[154:157], v[162:165], v[50:53]
	v_mfma_f32_16x16x32_bf16 v[38:41], v[146:149], v[170:173], v[38:41]
	v_mfma_f32_16x16x32_bf16 v[34:37], v[154:157], v[170:173], v[34:37]
	v_mfma_f32_16x16x32_bf16 v[22:25], v[146:149], v[178:181], v[22:25]
	v_mfma_f32_16x16x32_bf16 v[18:21], v[154:157], v[178:181], v[18:21]
	v_mfma_f32_16x16x32_bf16 v[6:9], v[146:149], v[194:197], v[6:9]
	v_mfma_f32_16x16x32_bf16 v[2:5], v[154:157], v[194:197], v[2:5]
	v_mfma_f32_16x16x32_bf16 v[54:57], v[150:153], v[166:169], v[54:57]
	v_mfma_f32_16x16x32_bf16 v[50:53], v[158:161], v[166:169], v[50:53]
	v_mfma_f32_16x16x32_bf16 v[38:41], v[150:153], v[174:177], v[38:41]
	v_mfma_f32_16x16x32_bf16 v[34:37], v[158:161], v[174:177], v[34:37]
	v_mfma_f32_16x16x32_bf16 v[22:25], v[150:153], v[182:185], v[22:25]
	v_mfma_f32_16x16x32_bf16 v[18:21], v[158:161], v[182:185], v[18:21]
	v_mfma_f32_16x16x32_bf16 v[6:9], v[150:153], v[222:225], v[6:9]
	v_mfma_f32_16x16x32_bf16 v[2:5], v[158:161], v[222:225], v[2:5]
	s_setprio 0
	s_barrier
	s_add_i32 s35, 0, 0x18000
	s_add_i32 s36, 0, 0x1c000
	v_add_u32_e32 v142, s35, v210
	v_add_u32_e32 v158, s36, v210
	ds_read_b128 v[130:133], v142
	ds_read_b128 v[134:137], v142 offset:1024
	ds_read_b128 v[138:141], v142 offset:2048
	ds_read_b128 v[142:145], v142 offset:3072
	ds_read_b128 v[146:149], v158
	ds_read_b128 v[150:153], v158 offset:1024
	ds_read_b128 v[154:157], v158 offset:2048
	ds_read_b128 v[158:161], v158 offset:3072
	s_add_u32 s8, s12, 0x80000
	s_addc_u32 s9, s13, 0
	s_mov_b32 m0, s27
	v_lshl_add_u64 v[230:231], s[8:9], 0, v[188:189]
	s_waitcnt lgkmcnt(0)
	ds_read_b128 v[162:165], v220 offset:32768
	ds_read_b128 v[166:169], v220 offset:33792
	ds_read_b128 v[170:173], v220 offset:34816
	ds_read_b128 v[174:177], v220 offset:35840
	ds_read_b128 v[178:181], v220 offset:36864
	ds_read_b128 v[182:185], v220 offset:37888
	ds_read_b128 v[194:197], v220 offset:38912
	ds_read_b128 v[222:225], v220 offset:39936
	global_load_lds_dwordx4 v[230:231], off
	s_mov_b32 m0, s28
	v_lshl_add_u64 v[230:231], s[8:9], 0, v[186:187]
	global_load_lds_dwordx4 v[230:231], off
	s_waitcnt vmcnt(8)
	s_waitcnt lgkmcnt(0)
	s_barrier
	s_setprio 1
	s_waitcnt lgkmcnt(0)
	v_mfma_f32_16x16x32_bf16 v[126:129], v[130:133], v[162:165], v[126:129]
	v_mfma_f32_16x16x32_bf16 v[122:125], v[138:141], v[162:165], v[122:125]
	v_mfma_f32_16x16x32_bf16 v[110:113], v[130:133], v[170:173], v[110:113]
	v_mfma_f32_16x16x32_bf16 v[106:109], v[138:141], v[170:173], v[106:109]
	v_mfma_f32_16x16x32_bf16 v[94:97], v[130:133], v[178:181], v[94:97]
	v_mfma_f32_16x16x32_bf16 v[90:93], v[138:141], v[178:181], v[90:93]
	v_mfma_f32_16x16x32_bf16 v[78:81], v[130:133], v[194:197], v[78:81]
	v_mfma_f32_16x16x32_bf16 v[74:77], v[138:141], v[194:197], v[74:77]
	v_mfma_f32_16x16x32_bf16 v[126:129], v[134:137], v[166:169], v[126:129]
	v_mfma_f32_16x16x32_bf16 v[122:125], v[142:145], v[166:169], v[122:125]
	v_mfma_f32_16x16x32_bf16 v[110:113], v[134:137], v[174:177], v[110:113]
	v_mfma_f32_16x16x32_bf16 v[106:109], v[142:145], v[174:177], v[106:109]
	v_mfma_f32_16x16x32_bf16 v[94:97], v[134:137], v[182:185], v[94:97]
	v_mfma_f32_16x16x32_bf16 v[90:93], v[142:145], v[182:185], v[90:93]
	v_mfma_f32_16x16x32_bf16 v[78:81], v[134:137], v[222:225], v[78:81]
	v_mfma_f32_16x16x32_bf16 v[74:77], v[142:145], v[222:225], v[74:77]
	s_setprio 0
	s_setprio 1
	v_mfma_f32_16x16x32_bf16 v[118:121], v[146:149], v[162:165], v[118:121]
	v_mfma_f32_16x16x32_bf16 v[114:117], v[154:157], v[162:165], v[114:117]
	v_mfma_f32_16x16x32_bf16 v[102:105], v[146:149], v[170:173], v[102:105]
	v_mfma_f32_16x16x32_bf16 v[98:101], v[154:157], v[170:173], v[98:101]
	v_mfma_f32_16x16x32_bf16 v[86:89], v[146:149], v[178:181], v[86:89]
	v_mfma_f32_16x16x32_bf16 v[82:85], v[154:157], v[178:181], v[82:85]
	v_mfma_f32_16x16x32_bf16 v[70:73], v[146:149], v[194:197], v[70:73]
	v_mfma_f32_16x16x32_bf16 v[66:69], v[154:157], v[194:197], v[66:69]
	v_mfma_f32_16x16x32_bf16 v[118:121], v[150:153], v[166:169], v[118:121]
	v_mfma_f32_16x16x32_bf16 v[114:117], v[158:161], v[166:169], v[114:117]
	v_mfma_f32_16x16x32_bf16 v[102:105], v[150:153], v[174:177], v[102:105]
	v_mfma_f32_16x16x32_bf16 v[98:101], v[158:161], v[174:177], v[98:101]
	v_mfma_f32_16x16x32_bf16 v[86:89], v[150:153], v[182:185], v[86:89]
	v_mfma_f32_16x16x32_bf16 v[82:85], v[158:161], v[182:185], v[82:85]
	v_mfma_f32_16x16x32_bf16 v[70:73], v[150:153], v[222:225], v[70:73]
	v_mfma_f32_16x16x32_bf16 v[66:69], v[158:161], v[222:225], v[66:69]
	s_setprio 0
	s_barrier
	s_add_i32 s8, s35, s14
	v_lshl_add_u64 v[198:199], v[198:199], 0, s[72:73]
	s_mov_b32 m0, s8
	ds_read_b128 v[162:165], v220 offset:49152
	ds_read_b128 v[166:169], v220 offset:50176
	ds_read_b128 v[170:173], v220 offset:51200
	ds_read_b128 v[174:177], v220 offset:52224
	ds_read_b128 v[178:181], v220 offset:53248
	ds_read_b128 v[182:185], v220 offset:54272
	ds_read_b128 v[194:197], v220 offset:55296
	ds_read_b128 v[222:225], v220 offset:56320
	global_load_lds_dwordx4 v[198:199], off
	s_add_i32 m0, s8, 0x2000
	s_add_u32 s8, s10, 0x80080
	v_lshl_add_u64 v[198:199], v[208:209], 0, s[72:73]
	s_addc_u32 s9, s11, 0
	s_add_i32 s10, s36, s14
	global_load_lds_dwordx4 v[198:199], off
	v_lshl_add_u64 v[198:199], s[8:9], 0, v[188:189]
	s_mov_b32 m0, s10
	s_nop 0
	global_load_lds_dwordx4 v[198:199], off
	v_lshl_add_u64 v[198:199], s[8:9], 0, v[186:187]
	s_add_i32 m0, s10, 0x2000
	s_nop 0
	global_load_lds_dwordx4 v[198:199], off
	v_lshl_add_u64 v[198:199], v[226:227], 0, s[72:73]
	s_mov_b32 m0, s31
	s_nop 0
	global_load_lds_dwordx4 v[198:199], off
	v_lshl_add_u64 v[198:199], v[228:229], 0, s[72:73]
	s_mov_b32 m0, s48
	s_nop 0
	global_load_lds_dwordx4 v[198:199], off
	s_waitcnt vmcnt(8)
	s_waitcnt lgkmcnt(0)
	s_barrier
	s_setprio 1
	s_waitcnt lgkmcnt(0)
	v_mfma_f32_16x16x32_bf16 v[62:65], v[130:133], v[162:165], v[62:65]
	v_mfma_f32_16x16x32_bf16 v[58:61], v[138:141], v[162:165], v[58:61]
	v_mfma_f32_16x16x32_bf16 v[46:49], v[130:133], v[170:173], v[46:49]
	v_mfma_f32_16x16x32_bf16 v[42:45], v[138:141], v[170:173], v[42:45]
	v_mfma_f32_16x16x32_bf16 v[30:33], v[130:133], v[178:181], v[30:33]
	v_mfma_f32_16x16x32_bf16 v[26:29], v[138:141], v[178:181], v[26:29]
	v_mfma_f32_16x16x32_bf16 v[14:17], v[130:133], v[194:197], v[14:17]
	v_mfma_f32_16x16x32_bf16 v[10:13], v[138:141], v[194:197], v[10:13]
	v_mfma_f32_16x16x32_bf16 v[62:65], v[134:137], v[166:169], v[62:65]
	v_mfma_f32_16x16x32_bf16 v[58:61], v[142:145], v[166:169], v[58:61]
	v_mfma_f32_16x16x32_bf16 v[46:49], v[134:137], v[174:177], v[46:49]
	v_mfma_f32_16x16x32_bf16 v[42:45], v[142:145], v[174:177], v[42:45]
	v_mfma_f32_16x16x32_bf16 v[30:33], v[134:137], v[182:185], v[30:33]
	v_mfma_f32_16x16x32_bf16 v[26:29], v[142:145], v[182:185], v[26:29]
	v_mfma_f32_16x16x32_bf16 v[14:17], v[134:137], v[222:225], v[14:17]
	v_mfma_f32_16x16x32_bf16 v[10:13], v[142:145], v[222:225], v[10:13]
	s_setprio 0
	s_setprio 1
	v_mfma_f32_16x16x32_bf16 v[54:57], v[146:149], v[162:165], v[54:57]
	v_mfma_f32_16x16x32_bf16 v[50:53], v[154:157], v[162:165], v[50:53]
	v_mfma_f32_16x16x32_bf16 v[38:41], v[146:149], v[170:173], v[38:41]
	v_mfma_f32_16x16x32_bf16 v[34:37], v[154:157], v[170:173], v[34:37]
	v_mfma_f32_16x16x32_bf16 v[22:25], v[146:149], v[178:181], v[22:25]
	v_mfma_f32_16x16x32_bf16 v[18:21], v[154:157], v[178:181], v[18:21]
	v_mfma_f32_16x16x32_bf16 v[6:9], v[146:149], v[194:197], v[6:9]
	v_mfma_f32_16x16x32_bf16 v[2:5], v[154:157], v[194:197], v[2:5]
	v_mfma_f32_16x16x32_bf16 v[54:57], v[150:153], v[166:169], v[54:57]
	v_mfma_f32_16x16x32_bf16 v[50:53], v[158:161], v[166:169], v[50:53]
	v_mfma_f32_16x16x32_bf16 v[38:41], v[150:153], v[174:177], v[38:41]
	v_mfma_f32_16x16x32_bf16 v[34:37], v[158:161], v[174:177], v[34:37]
	v_mfma_f32_16x16x32_bf16 v[22:25], v[150:153], v[182:185], v[22:25]
	v_mfma_f32_16x16x32_bf16 v[18:21], v[158:161], v[182:185], v[18:21]
	v_mfma_f32_16x16x32_bf16 v[6:9], v[150:153], v[222:225], v[6:9]
	v_mfma_f32_16x16x32_bf16 v[2:5], v[158:161], v[222:225], v[2:5]
	s_setprio 0
	s_barrier
	s_add_i32 s34, s34, 2
	s_add_u32 s23, s23, 0x100
	s_addc_u32 s33, s33, 0
	s_cmp_gt_u32 s34, 29
	s_mov_b64 s[8:9], s[0:1]
	s_cbranch_scc0 .LBB0_559
	s_and_b64 vcc, exec, s[54:55]
	s_cbranch_vccz .LBB0_562
	s_barrier

.LBB0_765:
	s_add_u32 s0, s14, 0x100
	s_addc_u32 s1, s15, 0
	s_add_i32 s33, 0, 0x10000
	s_cmpk_eq_i32 s22, 0x54
	s_cselect_b32 s21, s11, s1
	s_cselect_b32 s20, s10, s0
	s_cselect_b32 s17, s13, s18
	s_cselect_b32 s16, s12, s3
	s_add_i32 s34, 0, 0x14000
	v_add_u32_e32 v118, s33, v226
	v_add_u32_e32 v158, s34, v226
	ds_read_b128 v[82:85], v118
	ds_read_b128 v[94:97], v118 offset:1024
	ds_read_b128 v[106:109], v118 offset:2048
	ds_read_b128 v[118:121], v118 offset:3072
	ds_read_b128 v[130:133], v158
	ds_read_b128 v[142:145], v158 offset:1024
	ds_read_b128 v[150:153], v158 offset:2048
	ds_read_b128 v[158:161], v158 offset:3072
	v_lshl_add_u64 v[198:199], s[14:15], 0, v[190:191]
	s_add_i32 m0, s30, 0xc000
	s_waitcnt lgkmcnt(0)
	ds_read_b128 v[162:165], v231
	ds_read_b128 v[166:169], v231 offset:1024
	ds_read_b128 v[170:173], v231 offset:2048
	ds_read_b128 v[174:177], v231 offset:3072
	ds_read_b128 v[178:181], v231 offset:4096
	ds_read_b128 v[182:185], v231 offset:5120
	ds_read_b128 v[194:197], v231 offset:6144
	ds_read_b128 v[208:211], v231 offset:7168
	global_load_lds_dwordx4 v[198:199], off
	s_add_i32 m0, s30, 0xe000
	v_lshl_add_u64 v[198:199], s[14:15], 0, v[192:193]
	global_load_lds_dwordx4 v[198:199], off
	s_waitcnt vmcnt(8)
	s_waitcnt lgkmcnt(0)
	s_barrier
	s_setprio 1
	s_waitcnt lgkmcnt(0)
	v_mfma_f32_16x16x32_bf16 v[154:157], v[82:85], v[162:165], v[154:157]
	v_mfma_f32_16x16x32_bf16 v[146:149], v[106:109], v[162:165], v[146:149]
	v_mfma_f32_16x16x32_bf16 v[126:129], v[82:85], v[170:173], v[126:129]
	v_mfma_f32_16x16x32_bf16 v[122:125], v[106:109], v[170:173], v[122:125]
	v_mfma_f32_16x16x32_bf16 v[102:105], v[82:85], v[178:181], v[102:105]
	v_mfma_f32_16x16x32_bf16 v[98:101], v[106:109], v[178:181], v[98:101]
	v_mfma_f32_16x16x32_bf16 v[78:81], v[82:85], v[194:197], v[78:81]
	v_mfma_f32_16x16x32_bf16 v[74:77], v[106:109], v[194:197], v[74:77]
	v_mfma_f32_16x16x32_bf16 v[154:157], v[94:97], v[166:169], v[154:157]
	v_mfma_f32_16x16x32_bf16 v[146:149], v[118:121], v[166:169], v[146:149]
	v_mfma_f32_16x16x32_bf16 v[126:129], v[94:97], v[174:177], v[126:129]
	v_mfma_f32_16x16x32_bf16 v[122:125], v[118:121], v[174:177], v[122:125]
	v_mfma_f32_16x16x32_bf16 v[102:105], v[94:97], v[182:185], v[102:105]
	v_mfma_f32_16x16x32_bf16 v[98:101], v[118:121], v[182:185], v[98:101]
	v_mfma_f32_16x16x32_bf16 v[78:81], v[94:97], v[208:211], v[78:81]
	v_mfma_f32_16x16x32_bf16 v[74:77], v[118:121], v[208:211], v[74:77]
	s_setprio 0
	s_setprio 1
	v_mfma_f32_16x16x32_bf16 v[138:141], v[130:133], v[162:165], v[138:141]
	v_mfma_f32_16x16x32_bf16 v[134:137], v[150:153], v[162:165], v[134:137]
	v_mfma_f32_16x16x32_bf16 v[114:117], v[130:133], v[170:173], v[114:117]
	v_mfma_f32_16x16x32_bf16 v[110:113], v[150:153], v[170:173], v[110:113]
	v_mfma_f32_16x16x32_bf16 v[90:93], v[130:133], v[178:181], v[90:93]
	v_mfma_f32_16x16x32_bf16 v[86:89], v[150:153], v[178:181], v[86:89]
	v_mfma_f32_16x16x32_bf16 v[70:73], v[130:133], v[194:197], v[70:73]
	v_mfma_f32_16x16x32_bf16 v[66:69], v[150:153], v[194:197], v[66:69]
	v_mfma_f32_16x16x32_bf16 v[138:141], v[142:145], v[166:169], v[138:141]
	v_mfma_f32_16x16x32_bf16 v[134:137], v[158:161], v[166:169], v[134:137]
	v_mfma_f32_16x16x32_bf16 v[114:117], v[142:145], v[174:177], v[114:117]
	v_mfma_f32_16x16x32_bf16 v[110:113], v[158:161], v[174:177], v[110:113]
	v_mfma_f32_16x16x32_bf16 v[90:93], v[142:145], v[182:185], v[90:93]
	v_mfma_f32_16x16x32_bf16 v[86:89], v[158:161], v[182:185], v[86:89]
	v_mfma_f32_16x16x32_bf16 v[70:73], v[142:145], v[208:211], v[70:73]
	v_mfma_f32_16x16x32_bf16 v[66:69], v[158:161], v[208:211], v[66:69]
	s_setprio 0
	s_barrier
	s_add_i32 s14, s33, s29
	v_lshl_add_u64 v[198:199], s[16:17], 0, v[188:189]
	s_mov_b32 m0, s14
	ds_read_b128 v[162:165], v231 offset:16384
	ds_read_b128 v[166:169], v231 offset:17408
	ds_read_b128 v[170:173], v231 offset:18432
	ds_read_b128 v[174:177], v231 offset:19456
	ds_read_b128 v[178:181], v231 offset:20480
	ds_read_b128 v[182:185], v231 offset:21504
	ds_read_b128 v[194:197], v231 offset:22528
	ds_read_b128 v[208:211], v231 offset:23552
	global_load_lds_dwordx4 v[198:199], off
	s_add_i32 m0, s14, 0x2000
	s_add_u32 s14, s16, 0x160000
	v_lshl_add_u64 v[212:213], s[16:17], 0, v[186:187]
	s_addc_u32 s15, s17, 0
	s_add_i32 s33, s34, s29
	global_load_lds_dwordx4 v[212:213], off
	v_lshl_add_u64 v[214:215], s[14:15], 0, v[188:189]
	s_mov_b32 m0, s33
	v_lshl_add_u64 v[216:217], s[20:21], 0, v[186:187]
	global_load_lds_dwordx4 v[214:215], off
	v_lshl_add_u64 v[214:215], s[14:15], 0, v[186:187]
	s_add_i32 m0, s33, 0x2000
	s_nop 0
	global_load_lds_dwordx4 v[214:215], off
	v_lshl_add_u64 v[214:215], s[20:21], 0, v[188:189]
	s_mov_b32 m0, s30
	s_nop 0
	global_load_lds_dwordx4 v[214:215], off
	s_mov_b32 m0, s31
	s_nop 0
	global_load_lds_dwordx4 v[216:217], off
	s_waitcnt vmcnt(8)
	s_waitcnt lgkmcnt(0)
	s_barrier
	s_setprio 1
	s_waitcnt lgkmcnt(0)
	v_mfma_f32_16x16x32_bf16 v[62:65], v[82:85], v[162:165], v[62:65]
	v_mfma_f32_16x16x32_bf16 v[58:61], v[106:109], v[162:165], v[58:61]
	v_mfma_f32_16x16x32_bf16 v[46:49], v[82:85], v[170:173], v[46:49]
	v_mfma_f32_16x16x32_bf16 v[42:45], v[106:109], v[170:173], v[42:45]
	v_mfma_f32_16x16x32_bf16 v[30:33], v[82:85], v[178:181], v[30:33]
	v_mfma_f32_16x16x32_bf16 v[26:29], v[106:109], v[178:181], v[26:29]
	v_mfma_f32_16x16x32_bf16 v[14:17], v[82:85], v[194:197], v[14:17]
	v_mfma_f32_16x16x32_bf16 v[10:13], v[106:109], v[194:197], v[10:13]
	v_mfma_f32_16x16x32_bf16 v[62:65], v[94:97], v[166:169], v[62:65]
	v_mfma_f32_16x16x32_bf16 v[58:61], v[118:121], v[166:169], v[58:61]
	v_mfma_f32_16x16x32_bf16 v[46:49], v[94:97], v[174:177], v[46:49]
	v_mfma_f32_16x16x32_bf16 v[42:45], v[118:121], v[174:177], v[42:45]
	v_mfma_f32_16x16x32_bf16 v[30:33], v[94:97], v[182:185], v[30:33]
	v_mfma_f32_16x16x32_bf16 v[26:29], v[118:121], v[182:185], v[26:29]
	v_mfma_f32_16x16x32_bf16 v[14:17], v[94:97], v[208:211], v[14:17]
	v_mfma_f32_16x16x32_bf16 v[10:13], v[118:121], v[208:211], v[10:13]
	s_setprio 0
	s_setprio 1
	v_mfma_f32_16x16x32_bf16 v[54:57], v[130:133], v[162:165], v[54:57]
	v_mfma_f32_16x16x32_bf16 v[50:53], v[150:153], v[162:165], v[50:53]
	v_mfma_f32_16x16x32_bf16 v[38:41], v[130:133], v[170:173], v[38:41]
	v_mfma_f32_16x16x32_bf16 v[34:37], v[150:153], v[170:173], v[34:37]
	v_mfma_f32_16x16x32_bf16 v[22:25], v[130:133], v[178:181], v[22:25]
	v_mfma_f32_16x16x32_bf16 v[18:21], v[150:153], v[178:181], v[18:21]
	v_mfma_f32_16x16x32_bf16 v[6:9], v[130:133], v[194:197], v[6:9]
	v_mfma_f32_16x16x32_bf16 v[2:5], v[150:153], v[194:197], v[2:5]
	v_mfma_f32_16x16x32_bf16 v[54:57], v[142:145], v[166:169], v[54:57]
	v_mfma_f32_16x16x32_bf16 v[50:53], v[158:161], v[166:169], v[50:53]
	v_mfma_f32_16x16x32_bf16 v[38:41], v[142:145], v[174:177], v[38:41]
	v_mfma_f32_16x16x32_bf16 v[34:37], v[158:161], v[174:177], v[34:37]
	v_mfma_f32_16x16x32_bf16 v[22:25], v[142:145], v[182:185], v[22:25]
	v_mfma_f32_16x16x32_bf16 v[18:21], v[158:161], v[182:185], v[18:21]
	v_mfma_f32_16x16x32_bf16 v[6:9], v[142:145], v[208:211], v[6:9]
	v_mfma_f32_16x16x32_bf16 v[2:5], v[158:161], v[208:211], v[2:5]
	s_setprio 0
	s_barrier
	s_add_i32 s33, 0, 0x18000
	s_add_i32 s34, 0, 0x1c000
	v_add_u32_e32 v118, s33, v226
	v_add_u32_e32 v158, s34, v226
	ds_read_b128 v[82:85], v118
	ds_read_b128 v[94:97], v118 offset:1024
	ds_read_b128 v[106:109], v118 offset:2048
	ds_read_b128 v[118:121], v118 offset:3072
	ds_read_b128 v[130:133], v158
	ds_read_b128 v[142:145], v158 offset:1024
	ds_read_b128 v[150:153], v158 offset:2048
	ds_read_b128 v[158:161], v158 offset:3072
	s_add_u32 s14, s20, 0x160000
	s_addc_u32 s15, s21, 0
	s_mov_b32 m0, s36
	v_lshl_add_u64 v[218:219], s[14:15], 0, v[188:189]
	s_waitcnt lgkmcnt(0)
	ds_read_b128 v[162:165], v231 offset:32768
	ds_read_b128 v[166:169], v231 offset:33792
	ds_read_b128 v[170:173], v231 offset:34816
	ds_read_b128 v[174:177], v231 offset:35840
	ds_read_b128 v[178:181], v231 offset:36864
	ds_read_b128 v[182:185], v231 offset:37888
	ds_read_b128 v[194:197], v231 offset:38912
	ds_read_b128 v[208:211], v231 offset:39936
	global_load_lds_dwordx4 v[218:219], off
	s_mov_b32 m0, s37
	v_lshl_add_u64 v[218:219], s[14:15], 0, v[186:187]
	global_load_lds_dwordx4 v[218:219], off
	s_waitcnt vmcnt(8)
	s_waitcnt lgkmcnt(0)
	s_barrier
	s_setprio 1
	s_waitcnt lgkmcnt(0)
	v_mfma_f32_16x16x32_bf16 v[154:157], v[82:85], v[162:165], v[154:157]
	v_mfma_f32_16x16x32_bf16 v[146:149], v[106:109], v[162:165], v[146:149]
	v_mfma_f32_16x16x32_bf16 v[126:129], v[82:85], v[170:173], v[126:129]
	v_mfma_f32_16x16x32_bf16 v[122:125], v[106:109], v[170:173], v[122:125]
	v_mfma_f32_16x16x32_bf16 v[102:105], v[82:85], v[178:181], v[102:105]
	v_mfma_f32_16x16x32_bf16 v[98:101], v[106:109], v[178:181], v[98:101]
	v_mfma_f32_16x16x32_bf16 v[78:81], v[82:85], v[194:197], v[78:81]
	v_mfma_f32_16x16x32_bf16 v[74:77], v[106:109], v[194:197], v[74:77]
	v_mfma_f32_16x16x32_bf16 v[154:157], v[94:97], v[166:169], v[154:157]
	v_mfma_f32_16x16x32_bf16 v[146:149], v[118:121], v[166:169], v[146:149]
	v_mfma_f32_16x16x32_bf16 v[126:129], v[94:97], v[174:177], v[126:129]
	v_mfma_f32_16x16x32_bf16 v[122:125], v[118:121], v[174:177], v[122:125]
	v_mfma_f32_16x16x32_bf16 v[102:105], v[94:97], v[182:185], v[102:105]
	v_mfma_f32_16x16x32_bf16 v[98:101], v[118:121], v[182:185], v[98:101]
	v_mfma_f32_16x16x32_bf16 v[78:81], v[94:97], v[208:211], v[78:81]
	v_mfma_f32_16x16x32_bf16 v[74:77], v[118:121], v[208:211], v[74:77]
	s_setprio 0
	s_setprio 1
	v_mfma_f32_16x16x32_bf16 v[138:141], v[130:133], v[162:165], v[138:141]
	v_mfma_f32_16x16x32_bf16 v[134:137], v[150:153], v[162:165], v[134:137]
	v_mfma_f32_16x16x32_bf16 v[114:117], v[130:133], v[170:173], v[114:117]
	v_mfma_f32_16x16x32_bf16 v[110:113], v[150:153], v[170:173], v[110:113]
	v_mfma_f32_16x16x32_bf16 v[90:93], v[130:133], v[178:181], v[90:93]
	v_mfma_f32_16x16x32_bf16 v[86:89], v[150:153], v[178:181], v[86:89]
	v_mfma_f32_16x16x32_bf16 v[70:73], v[130:133], v[194:197], v[70:73]
	v_mfma_f32_16x16x32_bf16 v[66:69], v[150:153], v[194:197], v[66:69]
	v_mfma_f32_16x16x32_bf16 v[138:141], v[142:145], v[166:169], v[138:141]
	v_mfma_f32_16x16x32_bf16 v[134:137], v[158:161], v[166:169], v[134:137]
	v_mfma_f32_16x16x32_bf16 v[114:117], v[142:145], v[174:177], v[114:117]
	v_mfma_f32_16x16x32_bf16 v[110:113], v[158:161], v[174:177], v[110:113]
	v_mfma_f32_16x16x32_bf16 v[90:93], v[142:145], v[182:185], v[90:93]
	v_mfma_f32_16x16x32_bf16 v[86:89], v[158:161], v[182:185], v[86:89]
	v_mfma_f32_16x16x32_bf16 v[70:73], v[142:145], v[208:211], v[70:73]
	v_mfma_f32_16x16x32_bf16 v[66:69], v[158:161], v[208:211], v[66:69]
	s_setprio 0
	s_barrier
	s_add_i32 s14, s33, s29
	v_lshl_add_u64 v[198:199], v[198:199], 0, s[72:73]
	s_mov_b32 m0, s14
	ds_read_b128 v[162:165], v231 offset:49152
	ds_read_b128 v[166:169], v231 offset:50176
	ds_read_b128 v[170:173], v231 offset:51200
	ds_read_b128 v[174:177], v231 offset:52224
	ds_read_b128 v[178:181], v231 offset:53248
	ds_read_b128 v[182:185], v231 offset:54272
	ds_read_b128 v[194:197], v231 offset:55296
	ds_read_b128 v[208:211], v231 offset:56320
	global_load_lds_dwordx4 v[198:199], off
	s_add_i32 m0, s14, 0x2000
	s_add_u32 s14, s16, 0x160080
	v_lshl_add_u64 v[198:199], v[212:213], 0, s[72:73]
	s_addc_u32 s15, s17, 0
	s_add_i32 s16, s34, s29
	global_load_lds_dwordx4 v[198:199], off
	v_lshl_add_u64 v[198:199], s[14:15], 0, v[188:189]
	s_mov_b32 m0, s16
	s_nop 0
	global_load_lds_dwordx4 v[198:199], off
	v_lshl_add_u64 v[198:199], s[14:15], 0, v[186:187]
	s_add_i32 m0, s16, 0x2000
	s_nop 0
	global_load_lds_dwordx4 v[198:199], off
	v_lshl_add_u64 v[198:199], v[214:215], 0, s[72:73]
	s_mov_b32 m0, s49
	s_nop 0
	global_load_lds_dwordx4 v[198:199], off
	v_lshl_add_u64 v[198:199], v[216:217], 0, s[72:73]
	s_mov_b32 m0, s50
	s_nop 0
	global_load_lds_dwordx4 v[198:199], off
	s_waitcnt vmcnt(8)
	s_waitcnt lgkmcnt(0)
	s_barrier
	s_setprio 1
	s_waitcnt lgkmcnt(0)
	v_mfma_f32_16x16x32_bf16 v[62:65], v[82:85], v[162:165], v[62:65]
	v_mfma_f32_16x16x32_bf16 v[58:61], v[106:109], v[162:165], v[58:61]
	v_mfma_f32_16x16x32_bf16 v[46:49], v[82:85], v[170:173], v[46:49]
	v_mfma_f32_16x16x32_bf16 v[42:45], v[106:109], v[170:173], v[42:45]
	v_mfma_f32_16x16x32_bf16 v[30:33], v[82:85], v[178:181], v[30:33]
	v_mfma_f32_16x16x32_bf16 v[26:29], v[106:109], v[178:181], v[26:29]
	v_mfma_f32_16x16x32_bf16 v[14:17], v[82:85], v[194:197], v[14:17]
	v_mfma_f32_16x16x32_bf16 v[10:13], v[106:109], v[194:197], v[10:13]
	v_mfma_f32_16x16x32_bf16 v[62:65], v[94:97], v[166:169], v[62:65]
	v_mfma_f32_16x16x32_bf16 v[58:61], v[118:121], v[166:169], v[58:61]
	v_mfma_f32_16x16x32_bf16 v[46:49], v[94:97], v[174:177], v[46:49]
	v_mfma_f32_16x16x32_bf16 v[42:45], v[118:121], v[174:177], v[42:45]
	v_mfma_f32_16x16x32_bf16 v[30:33], v[94:97], v[182:185], v[30:33]
	v_mfma_f32_16x16x32_bf16 v[26:29], v[118:121], v[182:185], v[26:29]
	v_mfma_f32_16x16x32_bf16 v[14:17], v[94:97], v[208:211], v[14:17]
	v_mfma_f32_16x16x32_bf16 v[10:13], v[118:121], v[208:211], v[10:13]
	s_setprio 0
	s_setprio 1
	v_mfma_f32_16x16x32_bf16 v[54:57], v[130:133], v[162:165], v[54:57]
	v_mfma_f32_16x16x32_bf16 v[50:53], v[150:153], v[162:165], v[50:53]
	v_mfma_f32_16x16x32_bf16 v[38:41], v[130:133], v[170:173], v[38:41]
	v_mfma_f32_16x16x32_bf16 v[34:37], v[150:153], v[170:173], v[34:37]
	v_mfma_f32_16x16x32_bf16 v[22:25], v[130:133], v[178:181], v[22:25]
	v_mfma_f32_16x16x32_bf16 v[18:21], v[150:153], v[178:181], v[18:21]
	v_mfma_f32_16x16x32_bf16 v[6:9], v[130:133], v[194:197], v[6:9]
	v_mfma_f32_16x16x32_bf16 v[2:5], v[150:153], v[194:197], v[2:5]
	v_mfma_f32_16x16x32_bf16 v[54:57], v[142:145], v[166:169], v[54:57]
	v_mfma_f32_16x16x32_bf16 v[50:53], v[158:161], v[166:169], v[50:53]
	v_mfma_f32_16x16x32_bf16 v[38:41], v[142:145], v[174:177], v[38:41]
	v_mfma_f32_16x16x32_bf16 v[34:37], v[158:161], v[174:177], v[34:37]
	v_mfma_f32_16x16x32_bf16 v[22:25], v[142:145], v[182:185], v[22:25]
	v_mfma_f32_16x16x32_bf16 v[18:21], v[158:161], v[182:185], v[18:21]
	v_mfma_f32_16x16x32_bf16 v[6:9], v[142:145], v[208:211], v[6:9]
	v_mfma_f32_16x16x32_bf16 v[2:5], v[158:161], v[208:211], v[2:5]
	s_setprio 0
	s_barrier
	s_add_i32 s22, s22, 2
	s_add_u32 s3, s3, 0x100
	s_addc_u32 s18, s18, 0
	s_cmpk_gt_u32 s22, 0x55
	s_mov_b64 s[14:15], s[0:1]
	s_cbranch_scc0 .LBB0_765
	s_and_b64 vcc, exec, s[46:47]
	s_cbranch_vccz .LBB0_768
	s_barrier
